# MLA tile loop: drop 24 v_mov_b64 register shuffles per tile (in-place exp/sum/pack, shared C-init)
# speedup vs baseline: 1.1908x; 1.1908x over previous
; #define LAS __attribute__((address_space(3)))
; template <int DQK, int DV, int FLAGS, int qp, int kp, int vts, int op> ...
;     ...
;         if (!skip) {
;             const LAS unsigned char* kb = lds + cur * BUF + prow * KROW + 16 * hi;
;             const LAS unsigned char* vb = lds + cur * BUF + KT_BYTES + r32 * VROW + 16 * hi;
;             f32x16 p0, p1;
;             bf16x8 kf[2][4];
; #pragma unroll
;             for (int i = 0; i < 2; ++i) { kf[0][2 * i] = *(const LAS bf16x8*)(kb + i * 32); kf[0][2 * i + 1] = *(const LAS bf16x8*)(kb + 32 * KROW + i * 32); }
;             const int nrel = qpos - kv0 - 8 * hi;
;             if (FLAGS & AF_ALIBI) { const float ab = -slope2 * (float)nrel - ((FLAGS & AF_ROBUST) ? 0.f : m);
; #pragma unroll
;                 for (int r = 0; r < 16; ++r) { const float c = (float)(16 * (r >> 3) + (r & 7)); p0[r] = __builtin_fmaf(slope2, c, ab); p1[r] = __builtin_fmaf(slope2, c + 32.f, ab); }
;             } else if (FLAGS & AF_ROBUST) {
; #pragma unroll
;                 for (int r = 0; r < 16; ++r) { p0[r] = 0.f; p1[r] = 0.f; }
;             } else { p0 = negm; p1 = negm; }
;             __builtin_amdgcn_sched_barrier(0);
; #pragma unroll
;             for (int c = 0; c < ND0 / 2; ++c) {
;                 if (c + 1 < ND0 / 2) {
; #pragma unroll
;                     for (int i = 0; i < 2; ++i) { kf[(c + 1) & 1][2 * i] = *(const LAS bf16x8*)(kb + (2 * c + 2 + i) * 32); kf[(c + 1) & 1][2 * i + 1] = *(const LAS bf16x8*)(kb + 32 * KROW + (2 * c + 2 + i) * 32); }
;                 }
; #pragma unroll
;                 for (int i = 0; i < 2; ++i) {
;                     p0 = __builtin_amdgcn_mfma_f32_32x32x16_bf16(kf[c & 1][2 * i], qr[2 * c + i], p0, 0, 0, 0);
;                     p1 = __builtin_amdgcn_mfma_f32_32x32x16_bf16(kf[c & 1][2 * i + 1], qr[2 * c + i], p1, 0, 0, 0);
;                 }
;                 __builtin_amdgcn_sched_barrier(0);
;             }
;             if (more) ATT_GLOAD((FLAGS & AF_REV) ? t - 1 : t + 1);
.LBB0_540:
	s_add_i32 s12, s3, -1
	s_and_b32 s80, s12, 1
	s_cmp_lt_i32 s3, s2
	s_cselect_b64 s[14:15], -1, 0
	v_cndmask_b32_e64 v64, 0, 1, s[14:15]
	s_sub_i32 s12, s91, 63
	s_cmp_gt_i32 s12, s88
	v_cmp_ne_u32_e64 s[12:13], 1, v64
	s_cbranch_scc1 .LBB0_559
	s_mul_i32 s14, s80, 0x5800
	s_add_i32 s16, s14, 0
	v_add3_u32 v116, s16, v169, v0
	ds_read_b128 v[80:83], v116
	ds_read_b128 v[96:99], v116 offset:32
	ds_read_b128 v[100:103], v116 offset:6656
	ds_read_b128 v[104:107], v116 offset:6688
	s_waitcnt lgkmcnt(3)
	v_mfma_f32_32x32x16_bf16 v[64:79], v[80:83], v[2:5], v[48:63]
	s_waitcnt lgkmcnt(2)
	v_mfma_f32_32x32x16_bf16 v[64:79], v[96:99], v[6:9], v[64:79]
	s_waitcnt lgkmcnt(1)
	v_mfma_f32_32x32x16_bf16 v[80:95], v[100:103], v[2:5], v[48:63]
	ds_read_b128 v[96:99], v116 offset:64
	ds_read_b128 v[100:103], v116 offset:96
	ds_read_b128 v[108:111], v116 offset:6720
	ds_read_b128 v[112:115], v116 offset:6752
	s_waitcnt lgkmcnt(4)
	v_mfma_f32_32x32x16_bf16 v[80:95], v[104:107], v[6:9], v[80:95]
	s_waitcnt lgkmcnt(3)
	v_mfma_f32_32x32x16_bf16 v[64:79], v[96:99], v[10:13], v[64:79]
	s_waitcnt lgkmcnt(1)
	v_mfma_f32_32x32x16_bf16 v[80:95], v[108:111], v[10:13], v[80:95]
	v_mfma_f32_32x32x16_bf16 v[64:79], v[100:103], v[128:131], v[64:79]
	ds_read_b128 v[96:99], v116 offset:128
	ds_read_b128 v[100:103], v116 offset:160
	ds_read_b128 v[104:107], v116 offset:6784
	ds_read_b128 v[108:111], v116 offset:6816
	s_waitcnt lgkmcnt(4)
	v_mfma_f32_32x32x16_bf16 v[80:95], v[112:115], v[128:131], v[80:95]
	s_waitcnt lgkmcnt(3)
	v_mfma_f32_32x32x16_bf16 v[64:79], v[96:99], v[132:135], v[64:79]
	s_waitcnt lgkmcnt(1)
	v_mfma_f32_32x32x16_bf16 v[80:95], v[104:107], v[132:135], v[80:95]
	v_mfma_f32_32x32x16_bf16 v[64:79], v[100:103], v[136:139], v[64:79]
	s_waitcnt lgkmcnt(0)
	v_mfma_f32_32x32x16_bf16 v[80:95], v[108:111], v[136:139], v[80:95]
	s_and_b64 vcc, exec, s[12:13]
	s_cbranch_vccnz .LBB0_547
	s_and_saveexec_b64 s[14:15], s[8:9]
	s_cbranch_execz .LBB0_544
	global_load_dwordx4 v[140:143], v[178:179], off

; template <int DQK, int DV, int FLAGS, int qp, int kp, int vts, int op> ...
;     ...
;             f32x2 rs2 = {0.f, 0.f};
; #pragma unroll
;             for (int r = 0; r < 16; ++r) { p0[r] = __builtin_amdgcn_exp2f(p0[r]); p1[r] = __builtin_amdgcn_exp2f(p1[r]); }
; #pragma unroll
;             for (int r = 0; r < 16; r += 2) { rs2 += (f32x2){p0[r], p0[r + 1]}; rs2 += (f32x2){p1[r], p1[r + 1]}; }
;             l += rs2.x + rs2.y;
;             bf16x8 pf[4];
;             pf[0] = pack_bf16x8(p0, 0); pf[1] = pack_bf16x8(p0, 8); pf[2] = pack_bf16x8(p1, 0); pf[3] = pack_bf16x8(p1, 8);
.LBB0_558:
	v_mov_b32_e32 v185, v48
	v_exp_f32_e32 v64, v64
	v_exp_f32_e32 v65, v65
	v_exp_f32_e32 v80, v80
	v_exp_f32_e32 v81, v81
	v_pk_add_f32 v[96:97], v[64:65], 0 op_sel_hi:[1,0]
	v_exp_f32_e32 v66, v66
	v_exp_f32_e32 v67, v67
	v_pk_add_f32 v[96:97], v[80:81], v[96:97]
	v_exp_f32_e32 v82, v82
	v_exp_f32_e32 v83, v83
	v_pk_add_f32 v[96:97], v[66:67], v[96:97]
	v_exp_f32_e32 v68, v68
	v_exp_f32_e32 v69, v69
	v_pk_add_f32 v[96:97], v[82:83], v[96:97]
	v_exp_f32_e32 v84, v84
	v_exp_f32_e32 v85, v85
	v_pk_add_f32 v[96:97], v[68:69], v[96:97]
	v_exp_f32_e32 v70, v70
	v_exp_f32_e32 v71, v71
	v_pk_add_f32 v[96:97], v[84:85], v[96:97]
	v_exp_f32_e32 v86, v86
	v_exp_f32_e32 v87, v87
	v_pk_add_f32 v[96:97], v[70:71], v[96:97]
	v_exp_f32_e32 v72, v72
	v_exp_f32_e32 v73, v73
	v_pk_add_f32 v[96:97], v[86:87], v[96:97]
	v_exp_f32_e32 v88, v88
	v_exp_f32_e32 v89, v89
	v_pk_add_f32 v[96:97], v[72:73], v[96:97]
	v_exp_f32_e32 v74, v74
	v_exp_f32_e32 v75, v75
	v_pk_add_f32 v[96:97], v[88:89], v[96:97]
	v_exp_f32_e32 v90, v90
	v_exp_f32_e32 v91, v91
	v_pk_add_f32 v[96:97], v[74:75], v[96:97]
	v_exp_f32_e32 v76, v76
	v_exp_f32_e32 v77, v77
	v_pk_add_f32 v[96:97], v[90:91], v[96:97]
	v_exp_f32_e32 v92, v92
	v_exp_f32_e32 v93, v93
	v_pk_add_f32 v[96:97], v[76:77], v[96:97]
	v_exp_f32_e32 v78, v78
	v_exp_f32_e32 v79, v79
	v_pk_add_f32 v[96:97], v[92:93], v[96:97]
	v_exp_f32_e32 v94, v94
	v_exp_f32_e32 v95, v95
	v_pk_add_f32 v[96:97], v[78:79], v[96:97]
	s_nop 0
	v_pk_add_f32 v[96:97], v[94:95], v[96:97]
	v_cvt_pk_bf16_f32 v64, v64, v65
	v_cvt_pk_bf16_f32 v65, v66, v67
	v_cvt_pk_bf16_f32 v66, v68, v69
	v_cvt_pk_bf16_f32 v67, v70, v71
	v_cvt_pk_bf16_f32 v68, v72, v73
	v_cvt_pk_bf16_f32 v69, v74, v75
	v_cvt_pk_bf16_f32 v70, v76, v77
	v_cvt_pk_bf16_f32 v71, v78, v79
	v_cvt_pk_bf16_f32 v72, v80, v81
	v_cvt_pk_bf16_f32 v73, v82, v83
	v_cvt_pk_bf16_f32 v74, v84, v85
	v_cvt_pk_bf16_f32 v75, v86, v87
	v_cvt_pk_bf16_f32 v76, v88, v89
	v_cvt_pk_bf16_f32 v77, v90, v91
	v_cvt_pk_bf16_f32 v78, v92, v93
	v_cvt_pk_bf16_f32 v79, v94, v95
	v_add_f32_e32 v48, v96, v97
	s_branch .Lmla_pv

; #define LAS __attribute__((address_space(3)))
; template <int DQK, int DV, int FLAGS, int qp, int kp, int vts, int op> ...
;     ...
;             l += rs2.x + rs2.y;
;             bf16x8 pf[4];
;             pf[0] = pack_bf16x8(p0, 0); pf[1] = pack_bf16x8(p0, 8); pf[2] = pack_bf16x8(p1, 0); pf[3] = pack_bf16x8(p1, 8);
;             __builtin_amdgcn_sched_barrier(0);
; #pragma unroll
;             for (int d = 0; d < NDB; ++d) {
;                 if (d + 1 < NDB) {
; #pragma unroll
;                     for (int ks = 0; ks < 4; ++ks) vf[(d + 1) & 1][ks] = *(const LAS bf16x8*)(vb + (d + 1) * 32 * VROW + ks * 32);
;                 }
; #pragma unroll
;                 for (int ks = 0; ks < 4; ++ks) o[d] = __builtin_amdgcn_mfma_f32_32x32x16_bf16(vf[d & 1][ks], pf[ks], o[d], 0, 0, 0);
;                 __builtin_amdgcn_sched_barrier(0);
;             }
.Lmla_pv:
	s_waitcnt lgkmcnt(3)
	v_mfma_f32_32x32x16_bf16 v[32:47], v[164:167], v[64:67], v[32:47]
	ds_read_b128 v[80:83], v184 offset:17920
	ds_read_b128 v[84:87], v184 offset:17952
	ds_read_b128 v[88:91], v184 offset:17984
	ds_read_b128 v[92:95], v184 offset:18016
	s_waitcnt lgkmcnt(6)
	v_mfma_f32_32x32x16_bf16 v[32:47], v[160:163], v[68:71], v[32:47]
	s_waitcnt lgkmcnt(5)
	v_mfma_f32_32x32x16_bf16 v[32:47], v[156:159], v[72:75], v[32:47]
	s_waitcnt lgkmcnt(4)
	v_mfma_f32_32x32x16_bf16 v[32:47], v[152:155], v[76:79], v[32:47]
	s_waitcnt lgkmcnt(3)
	v_mfma_f32_32x32x16_bf16 v[16:31], v[80:83], v[64:67], v[16:31]
	s_waitcnt lgkmcnt(2)
	v_mfma_f32_32x32x16_bf16 v[16:31], v[84:87], v[68:71], v[16:31]
	s_waitcnt lgkmcnt(1)
	v_mfma_f32_32x32x16_bf16 v[16:31], v[88:91], v[72:75], v[16:31]
	s_waitcnt lgkmcnt(0)
	v_mfma_f32_32x32x16_bf16 v[16:31], v[92:95], v[76:79], v[16:31]
	v_add_f32_e32 v175, v175, v48
	s_mov_b64 s[82:83], -1
	v_mov_b32_e32 v48, v185
	s_cbranch_execz .LBB0_560

; __global__ void __launch_bounds__(NTHREADS, 2) mega_fwd(Args args) {
	.amdhsa_kernel _Z8mega_fwd4Args
		.amdhsa_group_segment_fixed_size 0
		.amdhsa_private_segment_fixed_size 0
		.amdhsa_kernarg_size 536
		.amdhsa_user_sgpr_count 2
		.amdhsa_user_sgpr_dispatch_ptr 0
		.amdhsa_user_sgpr_queue_ptr 0
		.amdhsa_user_sgpr_kernarg_segment_ptr 1
		.amdhsa_user_sgpr_dispatch_id 0
		.amdhsa_user_sgpr_kernarg_preload_length 0
		.amdhsa_user_sgpr_kernarg_preload_offset 0
		.amdhsa_user_sgpr_private_segment_size 0
		.amdhsa_uses_dynamic_stack 0
		.amdhsa_enable_private_segment 0
		.amdhsa_system_sgpr_workgroup_id_x 1
		.amdhsa_system_sgpr_workgroup_id_y 0
		.amdhsa_system_sgpr_workgroup_id_z 0
		.amdhsa_system_sgpr_workgroup_info 0
		.amdhsa_system_vgpr_workitem_id 2
		.amdhsa_next_free_vgpr 256
		.amdhsa_next_free_sgpr 102
		.amdhsa_accum_offset 256
		.amdhsa_reserve_vcc 1
		.amdhsa_float_round_mode_32 0
		.amdhsa_float_round_mode_16_64 0
		.amdhsa_float_denorm_mode_32 3
		.amdhsa_float_denorm_mode_16_64 3
		.amdhsa_dx10_clamp 1
		.amdhsa_ieee_mode 1
		.amdhsa_fp16_overflow 0
		.amdhsa_tg_split 0
		.amdhsa_exception_fp_ieee_invalid_op 0
		.amdhsa_exception_fp_denorm_src 0
		.amdhsa_exception_fp_ieee_div_zero 0
		.amdhsa_exception_fp_ieee_overflow 0
		.amdhsa_exception_fp_ieee_underflow 0
		.amdhsa_exception_fp_ieee_inexact 0
		.amdhsa_exception_int_div_zero 0
	.end_amdhsa_kernel

; __global__ void __launch_bounds__(NTHREADS, 2) mega_fwd(Args args) {
.Lfunc_end0:
	.size	_Z8mega_fwd4Args, .Lfunc_end0-_Z8mega_fwd4Args
	.set _Z8mega_fwd4Args.num_vgpr, 256
	.set _Z8mega_fwd4Args.num_agpr, 0
	.set _Z8mega_fwd4Args.numbered_sgpr, 102
	.set _Z8mega_fwd4Args.num_named_barrier, 0
	.set _Z8mega_fwd4Args.private_seg_size, 0
	.set _Z8mega_fwd4Args.uses_vcc, 1
	.set _Z8mega_fwd4Args.uses_flat_scratch, 0
	.set _Z8mega_fwd4Args.has_dyn_sized_stack, 0
	.set _Z8mega_fwd4Args.has_recursion, 0
	.set _Z8mega_fwd4Args.has_indirect_call, 0

; __global__ void __launch_bounds__(NTHREADS, 2) mega_fwd(Args args) {
amdhsa.kernels:
  - .agpr_count:     0
    .args:
      - .offset:         0
        .size:           280
        .value_kind:     by_value
      - .offset:         280
        .size:           4
        .value_kind:     hidden_block_count_x
      - .offset:         284
        .size:           4
        .value_kind:     hidden_block_count_y
      - .offset:         288
        .size:           4
        .value_kind:     hidden_block_count_z
      - .offset:         292
        .size:           2
        .value_kind:     hidden_group_size_x
      - .offset:         294
        .size:           2
        .value_kind:     hidden_group_size_y
      - .offset:         296
        .size:           2
        .value_kind:     hidden_group_size_z
      - .offset:         298
        .size:           2
        .value_kind:     hidden_remainder_x
      - .offset:         300
        .size:           2
        .value_kind:     hidden_remainder_y
      - .offset:         302
        .size:           2
        .value_kind:     hidden_remainder_z
      - .offset:         320
        .size:           8
        .value_kind:     hidden_global_offset_x
      - .offset:         328
        .size:           8
        .value_kind:     hidden_global_offset_y
      - .offset:         336
        .size:           8
        .value_kind:     hidden_global_offset_z
      - .offset:         344
        .size:           2
        .value_kind:     hidden_grid_dims
      - .offset:         368
        .size:           8
        .value_kind:     hidden_multigrid_sync_arg
      - .offset:         400
        .size:           4
        .value_kind:     hidden_dynamic_lds_size
    .group_segment_fixed_size: 0
    .kernarg_segment_align: 8
    .kernarg_segment_size: 536
    .language:       OpenCL C
    .language_version:
      - 2
      - 0
    .max_flat_workgroup_size: 512
    .name:           _Z8mega_fwd4Args
    .private_segment_fixed_size: 0
    .sgpr_count:     108
    .sgpr_spill_count: 275
    .symbol:         _Z8mega_fwd4Args.kd
    .uniform_work_group_size: 1
    .uses_dynamic_stack: false
    .vgpr_count:     256
    .vgpr_spill_count: 0
    .wavefront_size: 64
